# selected stream: first-half exps issued in the shadow of the last QK MFMAs (in place of hazard nops) into spare registers, redone on the rare rescale path; on top of v36
# speedup vs baseline: 1.0129x; 1.0021x over previous
; #define LAS __attribute__((address_space(3)))
;     f4 s[2][2];
; #pragma unroll
;     for (int ch = 0; ch < 2; ++ch)
; #pragma unroll
;         for (int kt = 0; kt < 2; ++kt) { f4 t = (f4){colbias, colbias, colbias, colbias}; t = MFMA16(kf[ch][kt][0], bq[0], t); s[ch][kt] = MFMA16(kf[ch][kt][1], bq[1], t); }
;     float mx = -1e30f;
; #pragma unroll
;     for (int ch = 0; ch < 2; ++ch)
; #pragma unroll
;         for (int h = 0; h < 2; ++h) mx = fmaxf(mx, fmaxf(fmaxf(s[ch][h][0], s[ch][h][1]), fmaxf(s[ch][h][2], s[ch][h][3])));
;     if (__any(mx > a.m + MAX_SLACK)) {
;         mx = fmaxf(mx, __shfl_xor(mx, 16)); mx = fmaxf(mx, __shfl_xor(mx, 32));
;         const float mn = fmaxf(a.m, mx), alpha = fexp2(a.m - mn); a.m = mn; a.l *= alpha;
; #pragma unroll
;         for (int c = 0; c < 4; ++c) a.o[c] = a.o[c] * alpha;
;     }
;     float ps = 0.f; bf16x8 pb[2];
; #pragma unroll
;     for (int ch = 0; ch < 2; ++ch) { f4 p0, p1;
; #pragma unroll
;         for (int j = 0; j < 4; ++j) { p0[j] = fexp2(s[ch][0][j] - a.m); p1[j] = fexp2(s[ch][1][j] - a.m); ps += p0[j] + p1[j]; }
;         pb[ch] = pack8(p0, p1); }
;     a.l += ps;
; #pragma unroll
;     for (int ch = 0; ch < 2; ++ch)
; #pragma unroll
;         for (int c = 0; c < 4; ++c) a.o[c] = MFMA16(vf[ch][c], pb[ch], a.o[c]);
; __device__ __forceinline__ void nsa_block_task(Ctx& C, int task, bf16* ONSA_OUT) {
;     ...
;         stream_tiles<4>(C, src, 0, qb, bufs, [&](const LAS unsigned char* buf, int j) {
;             if ((j >> 5) != cw) { cw = j >> 5; aw0 = (unsigned)__builtin_amdgcn_readfirstlane((int)ANYM[cw]); aw1 = (unsigned)__builtin_amdgcn_readfirstlane((int)ANYM[8 + cw]); }
;             bool any[2]; any[0] = (aw0 >> (j & 31)) & 1u; any[1] = (aw1 >> (j & 31)) & 1u;
;             if (any[0] || any[1]) {
;                 bool mysel[2];
; #pragma unroll
;                 for (int cg = 0; cg < 2; ++cg) mysel[cg] = (SELM[(4 * cg + qi) * 8 + (j >> 5)] >> (j & 31)) & 1u;
;                 bf16x8 kf[2][2][2], vf[2][4]; { const int ll = launder_v(lane);
; #pragma unroll
;                     for (int ch = 0; ch < 2; ++ch) { tile_read_k(buf, ch, ll, kf[ch]); tile_read_v(buf, ch, ll, vf[ch]); } }
; #pragma unroll
;                 for (int cg = 0; cg < 2; ++cg) if (any[cg]) attn_tile64_full(a[cg], kf, vf, bq[cg], mysel[cg] ? 0.f : -3e30f);
.LBB0_1211:
	v_pk_add_f32 v[2:3], v[72:73], v[74:75]
	v_cvt_pk_bf16_f32 v140, v72, v73
	v_cvt_pk_bf16_f32 v141, v74, v75
	v_cvt_pk_bf16_f32 v142, v76, v77
	v_cvt_pk_bf16_f32 v143, v78, v79
	v_pk_add_f32 v[2:3], v[2:3], v[76:77]
	v_pk_add_f32 v[2:3], v[2:3], v[78:79]
	s_waitcnt lgkmcnt(4)
	v_mfma_f32_16x16x32_bf16 v[32:35], v[116:119], v[140:143], v[32:35]
	v_exp_f32_e32 v128, v128
	v_exp_f32_e32 v129, v129
	v_mfma_f32_16x16x32_bf16 v[28:31], v[112:115], v[140:143], v[28:31]
	v_exp_f32_e32 v130, v130
	v_exp_f32_e32 v131, v131
	v_mfma_f32_16x16x32_bf16 v[24:27], v[108:111], v[140:143], v[24:27]
	v_exp_f32_e32 v120, v120
	v_exp_f32_e32 v121, v121
	v_mfma_f32_16x16x32_bf16 v[20:23], v[104:107], v[140:143], v[20:23]
	v_exp_f32_e32 v122, v122
	v_exp_f32_e32 v123, v123
	v_pk_add_f32 v[2:3], v[2:3], v[128:129]
	v_pk_add_f32 v[2:3], v[2:3], v[130:131]
	v_cvt_pk_bf16_f32 v128, v128, v129
	v_cvt_pk_bf16_f32 v129, v130, v131
	v_cvt_pk_bf16_f32 v130, v120, v121
	v_cvt_pk_bf16_f32 v131, v122, v123
	v_pk_add_f32 v[2:3], v[2:3], v[120:121]
	v_pk_add_f32 v[2:3], v[2:3], v[122:123]
	s_waitcnt lgkmcnt(0)
	v_mfma_f32_16x16x32_bf16 v[32:35], v[96:99], v[128:131], v[32:35]
	v_mfma_f32_16x16x32_bf16 v[28:31], v[100:103], v[128:131], v[28:31]
	v_mfma_f32_16x16x32_bf16 v[24:27], v[92:95], v[128:131], v[24:27]
	v_mfma_f32_16x16x32_bf16 v[20:23], v[88:91], v[128:131], v[20:23]
	v_add_f32_e32 v0, v2, v3
	v_add_f32_e32 v168, v168, v0
.LBB0_1212:
.LBB0_1213:
.LBB0_1214:
	s_cmp_eq_u32 s48, 0
	s_cbranch_scc1 .LBB0_1225
	s_ff1_i32_b32 s39, s48
	s_bitset0_b32 s48, s39
	s_lshl_b32 s3, s39, 14
	s_add_i32 s36, s41, s3
	s_add_i32 s40, s35, s39
	s_bitcmp1_b32 s46, s39
	s_cselect_b64 s[24:25], -1, 0
	s_bitcmp1_b32 s47, s39
	s_cselect_b64 s[22:23], -1, 0
	s_andn2_b64 vcc, exec, s[24:25]
	v_add_u32_e32 v89, s36, v225
	v_add_u32_e32 v0, s36, v226
	ds_read_b128 v[140:143], v89
	ds_read_b128 v[144:147], v89 offset:2048
	ds_read_b128 v[148:151], v0
	ds_read_b128 v[128:131], v0 offset:2048
	ds_read_b128 v[136:139], v89 offset:4096
	ds_read_b128 v[124:127], v89 offset:6144
	ds_read_b128 v[132:135], v0 offset:4096
	ds_read_b128 v[120:123], v0 offset:6144
	ds_read_b128 v[116:119], v89 offset:8192
	ds_read_b128 v[112:115], v89 offset:10240
	ds_read_b128 v[108:111], v89 offset:12288
	ds_read_b128 v[104:107], v89 offset:14336
	ds_read_b128 v[96:99], v0 offset:8192
	ds_read_b128 v[100:103], v0 offset:10240
	ds_read_b128 v[92:95], v0 offset:12288
	ds_read_b128 v[88:91], v0 offset:14336
	s_cbranch_vccnz .LBB0_1222
	s_waitcnt lgkmcnt(15)
	v_bfe_i32 v0, v62, s40, 1
	v_bfi_b32 v156, v0, 0, v231
	v_sub_f32_e32 v156, v156, v170
	v_mov_b32_e32 v157, v156
	v_mov_b32_e32 v158, v156
	v_mov_b32_e32 v159, v156
	s_waitcnt lgkmcnt(12)
	s_nop 0
	v_mfma_f32_16x16x32_bf16 v[152:155], v[140:143], v[4:7], v[156:159]
	v_mfma_f32_16x16x32_bf16 v[160:163], v[148:151], v[8:11], v[152:155]
	v_mfma_f32_16x16x32_bf16 v[152:155], v[144:147], v[4:7], v[156:159]
	v_mfma_f32_16x16x32_bf16 v[164:167], v[128:131], v[8:11], v[152:155]
	s_nop 5
	v_max3_f32 v0, v160, v161, v162
	v_max3_f32 v0, v0, v163, s93
	s_waitcnt lgkmcnt(8)
	v_mfma_f32_16x16x32_bf16 v[152:155], v[136:139], v[4:7], v[156:159]
	v_max3_f32 v0, v0, v164, v165
	v_max3_f32 v0, v0, v166, v167
	v_mfma_f32_16x16x32_bf16 v[156:159], v[124:127], v[4:7], v[156:159]
	v_mfma_f32_16x16x32_bf16 v[152:155], v[132:135], v[8:11], v[152:155]
	v_mfma_f32_16x16x32_bf16 v[156:159], v[120:123], v[8:11], v[156:159]
	v_exp_f32_e32 v64, v160
	v_exp_f32_e32 v65, v161
	v_exp_f32_e32 v66, v162
	v_exp_f32_e32 v67, v163
	v_exp_f32_e32 v68, v164
	v_exp_f32_e32 v69, v165
	v_exp_f32_e32 v70, v166
	v_exp_f32_e32 v71, v167
	v_max3_f32 v0, v0, v152, v153
	v_max3_f32 v0, v0, v154, v155
	v_max3_f32 v0, v0, v156, v157
	v_max3_f32 v0, v0, v158, v159
	v_cmp_lt_f32_e32 vcc, 0x41000000, v0
	s_cbranch_vccnz .Lresc0
.LBB0_1221:
	v_pk_add_f32 v[172:173], v[64:65], v[66:67]
	v_cvt_pk_bf16_f32 v160, v64, v65
	v_cvt_pk_bf16_f32 v161, v66, v67
	v_cvt_pk_bf16_f32 v162, v68, v69
	v_cvt_pk_bf16_f32 v163, v70, v71
	v_pk_add_f32 v[172:173], v[172:173], v[68:69]
	v_pk_add_f32 v[172:173], v[172:173], v[70:71]
	s_waitcnt lgkmcnt(4)
	v_mfma_f32_16x16x32_bf16 v[52:55], v[116:119], v[160:163], v[52:55]
	v_exp_f32_e32 v152, v152
	v_exp_f32_e32 v153, v153
	v_mfma_f32_16x16x32_bf16 v[48:51], v[112:115], v[160:163], v[48:51]
	v_exp_f32_e32 v154, v154
	v_exp_f32_e32 v155, v155
	v_mfma_f32_16x16x32_bf16 v[44:47], v[108:111], v[160:163], v[44:47]
	v_exp_f32_e32 v156, v156
	v_exp_f32_e32 v157, v157
	v_mfma_f32_16x16x32_bf16 v[40:43], v[104:107], v[160:163], v[40:43]
	v_exp_f32_e32 v158, v158
	v_exp_f32_e32 v159, v159
	v_pk_add_f32 v[172:173], v[172:173], v[152:153]
	v_pk_add_f32 v[172:173], v[172:173], v[154:155]
	v_cvt_pk_bf16_f32 v152, v152, v153
	v_cvt_pk_bf16_f32 v153, v154, v155
	v_cvt_pk_bf16_f32 v154, v156, v157
	v_cvt_pk_bf16_f32 v155, v158, v159
	v_pk_add_f32 v[172:173], v[172:173], v[156:157]
	v_pk_add_f32 v[172:173], v[172:173], v[158:159]
	s_waitcnt lgkmcnt(0)
	v_mfma_f32_16x16x32_bf16 v[52:55], v[96:99], v[152:155], v[52:55]
	v_mfma_f32_16x16x32_bf16 v[48:51], v[100:103], v[152:155], v[48:51]
	v_mfma_f32_16x16x32_bf16 v[44:47], v[92:95], v[152:155], v[44:47]
	v_mfma_f32_16x16x32_bf16 v[40:43], v[88:91], v[152:155], v[40:43]
	v_add_f32_e32 v0, v172, v173
	v_add_f32_e32 v36, v36, v0
; __device__ __forceinline__ bf16x8 pack8(const f4& a, const f4& b) { return __builtin_bit_cast(bf16x8, pack8u(a, b)); }
; __device__ __forceinline__ float fexp2(float x) { return __builtin_amdgcn_exp2f(x); }
; #define MFMA16(a, b, c) __builtin_amdgcn_mfma_f32_16x16x32_bf16((a), (b), (c), 0, 0, 0)
;     f4 s[2][2];
; #pragma unroll
;     for (int ch = 0; ch < 2; ++ch)
; #pragma unroll
;         for (int kt = 0; kt < 2; ++kt) { f4 t = (f4){colbias, colbias, colbias, colbias}; t = MFMA16(kf[ch][kt][0], bq[0], t); s[ch][kt] = MFMA16(kf[ch][kt][1], bq[1], t); }
;     float mx = -1e30f;
; #pragma unroll
;     for (int ch = 0; ch < 2; ++ch)
; #pragma unroll
;         for (int h = 0; h < 2; ++h) mx = fmaxf(mx, fmaxf(fmaxf(s[ch][h][0], s[ch][h][1]), fmaxf(s[ch][h][2], s[ch][h][3])));
;     if (__any(mx > a.m + MAX_SLACK)) {
;         mx = fmaxf(mx, __shfl_xor(mx, 16)); mx = fmaxf(mx, __shfl_xor(mx, 32));
;         const float mn = fmaxf(a.m, mx), alpha = fexp2(a.m - mn); a.m = mn; a.l *= alpha;
; #pragma unroll
;         for (int c = 0; c < 4; ++c) a.o[c] = a.o[c] * alpha;
;     }
;     float ps = 0.f; bf16x8 pb[2];
; #pragma unroll
;     for (int ch = 0; ch < 2; ++ch) { f4 p0, p1;
; #pragma unroll
;         for (int j = 0; j < 4; ++j) { p0[j] = fexp2(s[ch][0][j] - a.m); p1[j] = fexp2(s[ch][1][j] - a.m); ps += p0[j] + p1[j]; }
;         pb[ch] = pack8(p0, p1); }
;     a.l += ps;
; #pragma unroll
;     for (int ch = 0; ch < 2; ++ch)
; #pragma unroll
;         for (int c = 0; c < 4; ++c) a.o[c] = MFMA16(vf[ch][c], pb[ch], a.o[c]);
.LBB0_1222:
	s_andn2_b64 vcc, exec, s[22:23]
	s_cbranch_vccnz .LBB0_1212
	s_waitcnt lgkmcnt(15)
	v_bfe_i32 v0, v63, s40, 1
	v_bfi_b32 v152, v0, 0, v231
	v_sub_f32_e32 v152, v152, v169
	v_mov_b32_e32 v153, v152
	v_mov_b32_e32 v154, v152
	v_mov_b32_e32 v155, v152
	s_waitcnt lgkmcnt(12)
	s_nop 0
	v_mfma_f32_16x16x32_bf16 v[140:143], v[140:143], v[12:15], v[152:155]
	v_mfma_f32_16x16x32_bf16 v[144:147], v[144:147], v[12:15], v[152:155]
	v_mfma_f32_16x16x32_bf16 v[140:143], v[148:151], v[16:19], v[140:143]
	v_mfma_f32_16x16x32_bf16 v[144:147], v[128:131], v[16:19], v[144:147]
	s_waitcnt lgkmcnt(8)
	v_mfma_f32_16x16x32_bf16 v[128:131], v[136:139], v[12:15], v[152:155]
	s_nop 5
	v_max3_f32 v0, v140, v141, v142
	v_max3_f32 v0, v0, v143, s93
	v_mfma_f32_16x16x32_bf16 v[124:127], v[124:127], v[12:15], v[152:155]
	v_max3_f32 v0, v0, v144, v145
	v_mfma_f32_16x16x32_bf16 v[128:131], v[132:135], v[16:19], v[128:131]
	v_max3_f32 v0, v0, v146, v147
	v_mfma_f32_16x16x32_bf16 v[120:123], v[120:123], v[16:19], v[124:127]
	v_exp_f32_e32 v72, v140
	v_exp_f32_e32 v73, v141
	v_exp_f32_e32 v74, v142
	v_exp_f32_e32 v75, v143
	v_exp_f32_e32 v76, v144
	v_exp_f32_e32 v77, v145
	v_exp_f32_e32 v78, v146
	v_exp_f32_e32 v79, v147
	v_max3_f32 v0, v0, v128, v129
	v_max3_f32 v0, v0, v130, v131
	v_max3_f32 v0, v0, v120, v121
	v_max3_f32 v0, v0, v122, v123
	v_cmp_lt_f32_e32 vcc, 0x41000000, v0
	s_cbranch_vccz .LBB0_1211
	ds_bpermute_b32 v2, v217, v0
	v_max_f32_e32 v0, v0, v0
	s_waitcnt lgkmcnt(0)
	v_max_f32_e32 v2, v2, v2
	v_max_f32_e32 v0, v0, v2
	ds_bpermute_b32 v2, v219, v0
	s_waitcnt lgkmcnt(0)
	v_max3_f32 v2, 0, v0, v2
	v_sub_f32_e32 v0, 0, v2
	v_exp_f32_e32 v0, v0
	v_add_f32_e32 v169, v169, v2
	v_sub_f32_e32 v140, v140, v2
	v_sub_f32_e32 v141, v141, v2
	v_sub_f32_e32 v142, v142, v2
	v_sub_f32_e32 v143, v143, v2
	v_sub_f32_e32 v144, v144, v2
	v_sub_f32_e32 v145, v145, v2
	v_sub_f32_e32 v146, v146, v2
	v_sub_f32_e32 v147, v147, v2
	v_sub_f32_e32 v128, v128, v2
	v_sub_f32_e32 v129, v129, v2
	v_sub_f32_e32 v130, v130, v2
	v_sub_f32_e32 v131, v131, v2
	v_sub_f32_e32 v120, v120, v2
	v_sub_f32_e32 v121, v121, v2
	v_sub_f32_e32 v122, v122, v2
	v_sub_f32_e32 v123, v123, v2
	v_mul_f32_e32 v168, v168, v0
	v_pk_mul_f32 v[34:35], v[34:35], v[0:1] op_sel_hi:[1,0]
	v_pk_mul_f32 v[32:33], v[32:33], v[0:1] op_sel_hi:[1,0]
	v_pk_mul_f32 v[30:31], v[30:31], v[0:1] op_sel_hi:[1,0]
	v_pk_mul_f32 v[28:29], v[28:29], v[0:1] op_sel_hi:[1,0]
	v_pk_mul_f32 v[26:27], v[26:27], v[0:1] op_sel_hi:[1,0]
	v_pk_mul_f32 v[24:25], v[24:25], v[0:1] op_sel_hi:[1,0]
	v_pk_mul_f32 v[22:23], v[22:23], v[0:1] op_sel_hi:[1,0]
	v_pk_mul_f32 v[20:21], v[20:21], v[0:1] op_sel_hi:[1,0]
	v_exp_f32_e32 v72, v140
	v_exp_f32_e32 v73, v141
	v_exp_f32_e32 v74, v142
	v_exp_f32_e32 v75, v143
	v_exp_f32_e32 v76, v144
	v_exp_f32_e32 v77, v145
	v_exp_f32_e32 v78, v146
	v_exp_f32_e32 v79, v147
	s_branch .LBB0_1211
.Lresc0:
	ds_bpermute_b32 v2, v217, v0
	v_max_f32_e32 v0, v0, v0
	s_waitcnt lgkmcnt(0)
	v_max_f32_e32 v2, v2, v2
	v_max_f32_e32 v0, v0, v2
	ds_bpermute_b32 v2, v219, v0
	s_waitcnt lgkmcnt(0)
	v_max3_f32 v2, 0, v0, v2
	v_sub_f32_e32 v0, 0, v2
	v_exp_f32_e32 v0, v0
	v_add_f32_e32 v170, v170, v2
	v_sub_f32_e32 v160, v160, v2
	v_sub_f32_e32 v161, v161, v2
	v_sub_f32_e32 v162, v162, v2
	v_sub_f32_e32 v163, v163, v2
	v_sub_f32_e32 v164, v164, v2
	v_sub_f32_e32 v165, v165, v2
	v_sub_f32_e32 v166, v166, v2
	v_sub_f32_e32 v167, v167, v2
	v_sub_f32_e32 v152, v152, v2
	v_sub_f32_e32 v153, v153, v2
	v_sub_f32_e32 v154, v154, v2
	v_sub_f32_e32 v155, v155, v2
	v_sub_f32_e32 v156, v156, v2
	v_sub_f32_e32 v157, v157, v2
	v_sub_f32_e32 v158, v158, v2
	v_sub_f32_e32 v159, v159, v2
	v_mul_f32_e32 v36, v36, v0
	v_pk_mul_f32 v[54:55], v[54:55], v[0:1] op_sel_hi:[1,0]
	v_pk_mul_f32 v[52:53], v[52:53], v[0:1] op_sel_hi:[1,0]
	v_pk_mul_f32 v[50:51], v[50:51], v[0:1] op_sel_hi:[1,0]
	v_pk_mul_f32 v[48:49], v[48:49], v[0:1] op_sel_hi:[1,0]
	v_pk_mul_f32 v[46:47], v[46:47], v[0:1] op_sel_hi:[1,0]
	v_pk_mul_f32 v[44:45], v[44:45], v[0:1] op_sel_hi:[1,0]
	v_pk_mul_f32 v[42:43], v[42:43], v[0:1] op_sel_hi:[1,0]
	v_pk_mul_f32 v[40:41], v[40:41], v[0:1] op_sel_hi:[1,0]
	v_exp_f32_e32 v64, v160
	v_exp_f32_e32 v65, v161
	v_exp_f32_e32 v66, v162
	v_exp_f32_e32 v67, v163
	v_exp_f32_e32 v68, v164
	v_exp_f32_e32 v69, v165
	v_exp_f32_e32 v70, v166
	v_exp_f32_e32 v71, v167
	s_branch .LBB0_1221
